# ln1_router: rows of the next token pair prefetched into spare registers during the current pair (was load-then-wait in the same iteration)
# baseline (speedup 1.0000x reference)
.LBB0_799:
	s_or_b64 exec, exec, s[0:1]
	s_and_b64 vcc, exec, s[92:93]
	s_waitcnt lgkmcnt(0)
	s_barrier
	s_cbranch_vccz .LBB0_804
	v_readlane_b32 s4, v253, 18
	v_ashrrev_i32_e32 v37, 31, v36
	v_readlane_b32 s5, v253, 19
	v_readlane_b32 s6, v253, 20
	v_readlane_b32 s7, v253, 21
	v_readlane_b32 s8, v253, 22
	v_readlane_b32 s9, v253, 23
	v_lshlrev_b64 v[0:1], 4, v[36:37]
	v_readlane_b32 s10, v253, 24
	v_readlane_b32 s11, v253, 25
	s_mov_b64 s[4:5], s[8:9]
	s_mov_b64 s[6:7], s[10:11]
	v_lshl_add_u64 v[32:33], s[4:5], 0, v[0:1]
	v_lshl_add_u64 v[34:35], s[6:7], 0, v[0:1]
	global_load_dwordx4 v[0:3], v[32:33], off
	global_load_dwordx4 v[4:7], v[32:33], off offset:1024
	global_load_dwordx4 v[8:11], v[34:35], off
	global_load_dwordx4 v[12:15], v[34:35], off offset:1024
	global_load_dwordx4 v[16:19], v[32:33], off offset:2048
	global_load_dwordx4 v[20:23], v[32:33], off offset:3072
	global_load_dwordx4 v[24:27], v[34:35], off offset:2048
	global_load_dwordx4 v[28:31], v[34:35], off offset:3072
	v_bfrev_b32_e32 v32, v36
	v_lshrrev_b32_e32 v38, 28, v32
	v_add_u32_e32 v32, 64, v246
	v_cmp_lt_i32_e32 vcc, v245, v32
	v_readlane_b32 s12, v253, 26
	s_mov_b64 s[0:1], 0x16000000
	v_cndmask_b32_e32 v33, v174, v245, vcc
	v_cmp_lt_i32_e32 vcc, v244, v32
	v_lshlrev_b32_e32 v82, 2, v33
	v_and_b32_e32 v39, 1, v36
	v_cndmask_b32_e32 v33, v174, v244, vcc
	v_cmp_lt_i32_e32 vcc, v243, v32
	v_lshlrev_b32_e32 v83, 2, v33
	v_readlane_b32 s13, v253, 27
	v_cndmask_b32_e32 v33, v174, v243, vcc
	v_cmp_lt_i32_e32 vcc, v242, v32
	v_lshlrev_b32_e32 v84, 2, v33
	v_mov_b64_e32 v[34:35], s[66:67]
	v_cndmask_b32_e32 v33, v174, v242, vcc
	v_cmp_lt_i32_e32 vcc, v241, v32
	v_lshlrev_b32_e32 v85, 2, v33
	s_mov_b32 s12, 0x30000
	v_cndmask_b32_e32 v33, v174, v241, vcc
	v_cmp_lt_i32_e32 vcc, v240, v32
	v_lshlrev_b32_e32 v86, 2, v33
	v_mad_u64_u32 v[34:35], s[12:13], v38, s12, v[34:35]
	v_cndmask_b32_e32 v32, v174, v240, vcc
	v_lshlrev_b32_e32 v87, 2, v32
	v_lshl_add_u64 v[32:33], v[36:37], 2, s[66:67]
	v_lshl_add_u64 v[32:33], v[32:33], 0, s[0:1]
	v_cmp_eq_u32_e64 s[0:1], 0, v39
	v_and_b32_e32 v39, 2, v36
	v_cmp_eq_u32_e64 s[4:5], 0, v39
	v_and_b32_e32 v39, 4, v36
	v_cmp_eq_u32_e64 s[6:7], 0, v39
	v_and_b32_e32 v39, 8, v36
	s_mov_b64 s[12:13], 0xc00000
	v_cmp_eq_u32_e64 s[8:9], 0, v39
	v_lshl_add_u64 v[34:35], v[34:35], 0, s[12:13]
	v_lshl_add_u64 v[38:39], v[36:37], 3, s[66:67]
	s_mov_b64 s[12:13], 0xf800000
	v_readlane_b32 s18, v253, 32
	v_lshl_add_u32 v88, v36, 4, 0
	v_cmp_gt_i32_e64 s[10:11], 16, v36
	v_lshl_add_u64 v[36:37], v[38:39], 0, s[12:13]
	s_mov_b64 s[12:13], 0x4000000
	v_lshl_add_u64 v[38:39], v[38:39], 0, s[12:13]
	v_mov_b32_e32 v89, 0x3727c5ac
	s_mov_b32 s24, 0xf800000
	v_mov_b32_e32 v90, 0x260
	s_mov_b32 s18, s80
	v_readlane_b32 s14, v253, 28
	v_readlane_b32 s15, v253, 29
	v_readlane_b32 s16, v253, 30
	v_readlane_b32 s17, v253, 31
	v_readlane_b32 s19, v253, 33
	s_mov_b32 s30, s18
	s_add_i32 s31, s30, s78
	s_cmp_lt_i32 s31, 0xc000
	s_cselect_b32 s31, s31, s30
	s_ashr_i32 s35, s30, 31
	s_mov_b32 s34, s30
	s_lshl_b64 s[34:35], s[34:35], 11
	s_ashr_i32 s37, s31, 31
	s_mov_b32 s36, s31
	s_lshl_b64 s[36:37], s[36:37], 11
	v_lshl_add_u64 v[40:41], v[36:37], 0, s[34:35]
	global_load_dwordx2 v[104:105], v[40:41], off
	global_load_dwordx2 v[106:107], v[40:41], off offset:512
	global_load_dwordx2 v[108:109], v[40:41], off offset:1024
	global_load_dwordx2 v[110:111], v[40:41], off offset:1536
	v_lshl_add_u64 v[40:41], v[36:37], 0, s[36:37]
	global_load_dwordx2 v[112:113], v[40:41], off
	global_load_dwordx2 v[114:115], v[40:41], off offset:512
	global_load_dwordx2 v[116:117], v[40:41], off offset:1024
	global_load_dwordx2 v[118:119], v[40:41], off offset:1536
	s_waitcnt vmcnt(0)
	s_branch .LBB0_802

.LBB0_802:
	s_add_i32 s25, s18, s78
	s_cmp_lt_i32 s25, 0xc000
	s_cselect_b32 s16, s25, s18
	s_ashr_i32 s19, s18, 31
	s_lshl_b64 s[20:21], s[18:19], 11
	s_ashr_i32 s17, s16, 31
	s_lshl_b64 s[22:23], s[16:17], 11
	s_waitcnt vmcnt(16)
	s_waitcnt lgkmcnt(0)
	v_mov_b64_e32 v[42:43], v[104:105]
	v_mov_b64_e32 v[44:45], v[106:107]
	v_mov_b64_e32 v[46:47], v[108:109]
	v_mov_b64_e32 v[50:51], v[110:111]
	v_mov_b64_e32 v[52:53], v[112:113]
	v_mov_b64_e32 v[54:55], v[114:115]
	v_mov_b64_e32 v[62:63], v[116:117]
	v_mov_b64_e32 v[72:73], v[118:119]
	s_add_i32 s30, s25, s78
	s_cmp_lt_i32 s30, 0xc000
	s_cbranch_scc0 .Lln1_nopf
	s_add_i32 s31, s30, s78
	s_cmp_lt_i32 s31, 0xc000
	s_cselect_b32 s31, s31, s30
	s_ashr_i32 s35, s30, 31
	s_mov_b32 s34, s30
	s_lshl_b64 s[34:35], s[34:35], 11
	s_ashr_i32 s37, s31, 31
	s_mov_b32 s36, s31
	s_lshl_b64 s[36:37], s[36:37], 11
	v_lshl_add_u64 v[40:41], v[36:37], 0, s[34:35]
	global_load_dwordx2 v[104:105], v[40:41], off
	global_load_dwordx2 v[106:107], v[40:41], off offset:512
	global_load_dwordx2 v[108:109], v[40:41], off offset:1024
	global_load_dwordx2 v[110:111], v[40:41], off offset:1536
	v_lshl_add_u64 v[40:41], v[36:37], 0, s[36:37]
	global_load_dwordx2 v[112:113], v[40:41], off
	global_load_dwordx2 v[114:115], v[40:41], off offset:512
	global_load_dwordx2 v[116:117], v[40:41], off offset:1024
	global_load_dwordx2 v[118:119], v[40:41], off offset:1536
.Lln1_nopf:
	s_lshl_b64 s[26:27], s[18:19], 10
	s_lshl_b64 s[28:29], s[16:17], 10
	v_lshlrev_b32_e32 v41, 16, v43
	v_lshlrev_b32_e32 v40, 16, v42
	v_and_b32_e32 v93, 0xffff0000, v43
	v_and_b32_e32 v92, 0xffff0000, v42
	v_lshlrev_b32_e32 v49, 16, v45
	v_lshlrev_b32_e32 v48, 16, v44
	v_and_b32_e32 v95, 0xffff0000, v45
	v_and_b32_e32 v94, 0xffff0000, v44
	v_lshlrev_b32_e32 v56, 16, v46
	v_and_b32_e32 v57, 0xffff0000, v46
	v_lshlrev_b32_e32 v58, 16, v47
	v_and_b32_e32 v59, 0xffff0000, v47
	v_pk_add_f32 v[42:43], v[40:41], v[92:93]
	v_lshlrev_b32_e32 v45, 16, v53
	v_lshlrev_b32_e32 v44, 16, v52
	v_and_b32_e32 v97, 0xffff0000, v53
	v_and_b32_e32 v96, 0xffff0000, v52
	v_pk_add_f32 v[46:47], v[48:49], v[94:95]
	v_lshlrev_b32_e32 v53, 16, v55
	v_lshlrev_b32_e32 v52, 16, v54
	v_and_b32_e32 v55, 0xffff0000, v55
	v_and_b32_e32 v54, 0xffff0000, v54
	v_lshlrev_b32_e32 v71, 16, v50
	v_and_b32_e32 v67, 0xffff0000, v50
	v_lshlrev_b32_e32 v69, 16, v51
	v_and_b32_e32 v65, 0xffff0000, v51
	v_add_f32_e32 v68, v56, v57
	v_add_f32_e32 v64, v58, v59
	v_add_f32_e32 v66, v42, v43
	v_pk_add_f32 v[42:43], v[44:45], v[96:97]
	v_pk_add_f32 v[50:51], v[52:53], v[54:55]
	v_pk_add_f32 v[46:47], v[46:47], v[46:47] op_sel:[0,1] op_sel_hi:[1,0]
	v_lshlrev_b32_e32 v60, 16, v62
	v_and_b32_e32 v61, 0xffff0000, v62
	v_lshlrev_b32_e32 v80, 16, v63
	v_and_b32_e32 v81, 0xffff0000, v63
	v_and_b32_e32 v75, 0xffff0000, v72
	v_pk_add_f32 v[62:63], v[68:69], v[64:65]
	v_add_f32_e32 v70, 0, v66
	v_add_f32_e32 v64, v42, v43
	v_mov_b32_e32 v47, v67
	v_pk_add_f32 v[42:43], v[50:51], v[50:51] op_sel:[0,1] op_sel_hi:[1,0]
	v_lshlrev_b32_e32 v79, 16, v72
	v_lshlrev_b32_e32 v77, 16, v73
	v_and_b32_e32 v73, 0xffff0000, v73
	v_add_f32_e32 v76, v60, v61
	v_add_f32_e32 v72, v80, v81
	v_add_f32_e32 v78, 0, v64
	v_pk_add_f32 v[46:47], v[70:71], v[46:47]
	v_mov_b32_e32 v43, v75
	v_pk_add_f32 v[50:51], v[76:77], v[72:73]
	v_pk_add_f32 v[46:47], v[46:47], v[62:63]
	v_pk_add_f32 v[42:43], v[78:79], v[42:43]
	v_add_f32_e32 v46, v46, v47
	v_pk_add_f32 v[42:43], v[42:43], v[50:51]
	ds_bpermute_b32 v47, v82, v46
	v_add_f32_e32 v42, v42, v43
	ds_bpermute_b32 v43, v82, v42
	s_waitcnt lgkmcnt(1)
	v_add_f32_e32 v46, v46, v47
	ds_bpermute_b32 v47, v83, v46
	s_waitcnt lgkmcnt(1)
	v_add_f32_e32 v42, v42, v43
	ds_bpermute_b32 v43, v83, v42
	s_waitcnt lgkmcnt(1)
	v_add_f32_e32 v46, v46, v47
	ds_bpermute_b32 v47, v84, v46
	s_waitcnt lgkmcnt(1)
	v_add_f32_e32 v42, v42, v43
	ds_bpermute_b32 v43, v84, v42
	s_waitcnt lgkmcnt(1)
	v_add_f32_e32 v46, v46, v47
	ds_bpermute_b32 v47, v85, v46
	s_waitcnt lgkmcnt(1)
	v_add_f32_e32 v42, v42, v43
	ds_bpermute_b32 v43, v85, v42
	s_waitcnt lgkmcnt(1)
	v_add_f32_e32 v46, v46, v47
	ds_bpermute_b32 v47, v86, v46
	s_waitcnt lgkmcnt(1)
	v_add_f32_e32 v42, v42, v43
	ds_bpermute_b32 v43, v86, v42
	s_waitcnt lgkmcnt(1)
	v_add_f32_e32 v46, v46, v47
	ds_bpermute_b32 v47, v87, v46
	s_waitcnt lgkmcnt(1)
	v_add_f32_e32 v42, v42, v43
	ds_bpermute_b32 v43, v87, v42
	s_waitcnt lgkmcnt(1)
	v_add_f32_e32 v64, v46, v47
	v_fmac_f32_e32 v92, 0xba800000, v64
	s_waitcnt lgkmcnt(0)
	v_add_f32_e32 v66, v42, v43
	v_fmac_f32_e32 v93, 0xba800000, v64
	v_fmac_f32_e32 v41, 0xba800000, v64
	v_fmac_f32_e32 v40, 0xba800000, v64
	v_fmac_f32_e32 v96, 0xba800000, v66
	v_fmac_f32_e32 v97, 0xba800000, v66
	v_fmac_f32_e32 v45, 0xba800000, v66
	v_mov_b32_e32 v42, v41
	v_mov_b32_e32 v43, v93
	v_mov_b32_e32 v41, v92
	v_fmac_f32_e32 v44, 0xba800000, v66
	v_pk_mul_f32 v[62:63], v[42:43], v[42:43]
	v_pk_mul_f32 v[92:93], v[40:41], v[40:41]
	v_mov_b32_e32 v46, v45
	v_mov_b32_e32 v47, v97
	v_mov_b32_e32 v45, v96
	v_fmac_f32_e32 v94, 0xba800000, v64
	v_fmac_f32_e32 v95, 0xba800000, v64
	v_fmac_f32_e32 v49, 0xba800000, v64
	v_pk_mov_b32 v[98:99], v[92:93], v[62:63] op_sel:[1,0]
	v_mov_b32_e32 v93, v63
	v_pk_mul_f32 v[62:63], v[46:47], v[46:47]
	v_pk_mul_f32 v[100:101], v[44:45], v[44:45]
	v_fmac_f32_e32 v48, 0xba800000, v64
	v_mov_b32_e32 v50, v49
	v_mov_b32_e32 v51, v95
	v_mov_b32_e32 v49, v94
	v_pk_add_f32 v[92:93], v[92:93], v[98:99]
	v_pk_mov_b32 v[98:99], v[100:101], v[62:63] op_sel:[1,0]
	v_mov_b32_e32 v101, v63
	v_pk_mul_f32 v[94:95], v[50:51], v[50:51]
	v_pk_mul_f32 v[96:97], v[48:49], v[48:49]
	v_pk_add_f32 v[62:63], v[98:99], v[100:101]
	v_fmac_f32_e32 v57, 0xba800000, v64
	v_pk_add_f32 v[98:99], v[62:63], v[62:63] op_sel_hi:[0,1]
	v_pk_mov_b32 v[62:63], v[96:97], v[94:95] op_sel:[1,0]
	v_mov_b32_e32 v97, v95
	v_fmac_f32_e32 v56, 0xba800000, v64
	v_fmac_f32_e32 v59, 0xba800000, v64
	v_fmac_f32_e32 v58, 0xba800000, v64
	v_fmac_f32_e32 v65, 0xba800000, v64
	v_fmac_f32_e32 v69, 0xba800000, v64
	v_fmac_f32_e32 v67, 0xba800000, v64
	v_fmac_f32_e32 v71, 0xba800000, v64
	v_mul_f32_e32 v64, v57, v57
	v_pk_add_f32 v[94:95], v[96:97], v[62:63]
	v_pk_fma_f32 v[100:101], v[56:57], v[56:57], v[64:65] op_sel_hi:[1,1,0]
	v_mul_f32_e32 v64, v59, v59
	v_mul_f32_e32 v68, v71, v71
	v_mul_f32_e32 v70, v67, v67
	v_mul_f32_e32 v72, v69, v69
	v_mul_f32_e32 v74, v65, v65
	v_pk_fma_f32 v[102:103], v[58:59], v[58:59], v[64:65] op_sel_hi:[1,1,0]
	v_pk_add_f32 v[92:93], v[92:93], v[92:93] op_sel:[0,1] op_sel_hi:[1,0]
	v_pk_add_f32 v[94:95], v[94:95], v[94:95] op_sel:[0,1] op_sel_hi:[1,0]
	v_mov_b32_e32 v101, v68
	v_mov_b32_e32 v103, v70
	v_mov_b32_e32 v93, v74
	v_mov_b32_e32 v95, v72
	v_pk_add_f32 v[100:101], v[100:101], v[102:103]
	v_pk_add_f32 v[92:93], v[92:93], v[94:95]
	v_fmac_f32_e32 v54, 0xba800000, v66
	v_pk_add_f32 v[92:93], v[100:101], v[92:93]
	v_fmac_f32_e32 v55, 0xba800000, v66
	v_fmac_f32_e32 v53, 0xba800000, v66
	v_add_f32_e32 v64, v92, v93
	v_fmac_f32_e32 v52, 0xba800000, v66
	v_mov_b32_e32 v62, v53
	v_mov_b32_e32 v63, v55
	v_mov_b32_e32 v53, v54
	ds_bpermute_b32 v68, v82, v64
	v_pk_mul_f32 v[96:97], v[62:63], v[62:63]
	v_pk_mul_f32 v[54:55], v[52:53], v[52:53]
	v_fmac_f32_e32 v60, 0xba800000, v66
	v_pk_mov_b32 v[92:93], v[54:55], v[96:97] op_sel:[1,0]
	v_mov_b32_e32 v55, v97
	v_pk_add_f32 v[54:55], v[92:93], v[54:55]
	v_fmac_f32_e32 v61, 0xba800000, v66
	v_pk_add_f32 v[54:55], v[54:55], v[54:55] op_sel_hi:[0,1]
	s_waitcnt lgkmcnt(0)
	v_add_f32_e32 v54, v64, v68
	ds_bpermute_b32 v64, v83, v54
	v_fmac_f32_e32 v80, 0xba800000, v66
	v_fmac_f32_e32 v81, 0xba800000, v66
	v_fmac_f32_e32 v73, 0xba800000, v66
	v_fmac_f32_e32 v77, 0xba800000, v66
	s_waitcnt lgkmcnt(0)
	v_add_f32_e32 v64, v54, v64
	ds_bpermute_b32 v68, v84, v64
	v_mul_f32_e32 v54, v60, v60
	v_pk_fma_f32 v[92:93], v[60:61], v[60:61], v[54:55] op_sel_hi:[1,1,0]
	v_mul_f32_e32 v54, v80, v80
	v_pk_fma_f32 v[94:95], v[80:81], v[80:81], v[54:55] op_sel_hi:[1,1,0]
	s_waitcnt lgkmcnt(0)
	v_add_f32_e32 v54, v64, v68
	ds_bpermute_b32 v64, v85, v54
	v_fmac_f32_e32 v75, 0xba800000, v66
	v_fmac_f32_e32 v79, 0xba800000, v66
	v_mul_f32_e32 v92, v79, v79
	v_mul_f32_e32 v94, v75, v75
	s_waitcnt lgkmcnt(0)
	v_add_f32_e32 v64, v54, v64
	ds_bpermute_b32 v66, v86, v64
	v_mul_f32_e32 v98, v77, v77
	v_mul_f32_e32 v54, v73, v73
	v_pk_add_f32 v[92:93], v[92:93], v[94:95]
	v_pk_add_f32 v[54:55], v[98:99], v[54:55]
	s_waitcnt lgkmcnt(0)
	v_add_f32_e32 v64, v64, v66
	ds_bpermute_b32 v66, v87, v64
	v_pk_add_f32 v[54:55], v[92:93], v[54:55]
	v_lshl_add_u64 v[96:97], v[38:39], 0, s[20:21]
	v_add_f32_e32 v54, v54, v55
	v_lshl_add_u64 v[98:99], v[38:39], 0, s[22:23]
	s_waitcnt lgkmcnt(0)
	v_add_f32_e32 v55, v64, v66
	ds_bpermute_b32 v66, v82, v54
	v_fmamk_f32 v55, v55, 0x3a800000, v89
	v_mul_f32_e32 v64, 0x4f800000, v55
	v_cmp_gt_f32_e32 vcc, s24, v55
	v_lshl_add_u64 v[92:93], v[32:33], 0, s[26:27]
	s_waitcnt lgkmcnt(0)
	v_add_f32_e32 v54, v54, v66
	ds_bpermute_b32 v66, v83, v54
	v_cndmask_b32_e32 v55, v55, v64, vcc
	v_sqrt_f32_e32 v64, v55
	v_lshl_add_u64 v[94:95], v[32:33], 0, s[28:29]
	s_waitcnt lgkmcnt(0)
	v_add_f32_e32 v54, v54, v66
	ds_bpermute_b32 v66, v84, v54
	v_add_u32_e32 v68, -1, v64
	v_fma_f32 v70, -v68, v64, v55
	v_cmp_ge_f32_e64 s[12:13], 0, v70
	v_add_u32_e32 v70, 1, v64
	s_waitcnt lgkmcnt(0)
	v_add_f32_e32 v54, v54, v66
	ds_bpermute_b32 v66, v85, v54
	v_cndmask_b32_e64 v68, v64, v68, s[12:13]
	v_fma_f32 v64, -v70, v64, v55
	v_cmp_lt_f32_e64 s[12:13], 0, v64
	s_waitcnt lgkmcnt(0)
	v_add_f32_e32 v54, v54, v66
	ds_bpermute_b32 v66, v86, v54
	v_cndmask_b32_e64 v64, v68, v70, s[12:13]
	v_mul_f32_e32 v68, 0x37800000, v64
	v_cndmask_b32_e32 v64, v64, v68, vcc
	v_cmp_class_f32_e32 vcc, v55, v90
	s_waitcnt lgkmcnt(0)
	v_add_f32_e32 v54, v54, v66
	ds_bpermute_b32 v66, v87, v54
	v_cndmask_b32_e32 v55, v64, v55, vcc
	v_div_scale_f32 v64, s[12:13], v55, v55, 1.0
	v_rcp_f32_e32 v68, v64
	s_waitcnt lgkmcnt(0)
	v_add_f32_e32 v54, v54, v66
	v_fmamk_f32 v54, v54, 0x3a800000, v89
	v_mul_f32_e32 v66, 0x4f800000, v54
	v_cmp_gt_f32_e64 s[12:13], s24, v54
	v_fma_f32 v70, -v64, v68, 1.0
	v_fmac_f32_e32 v68, v70, v68
	v_cndmask_b32_e64 v54, v54, v66, s[12:13]
	v_div_scale_f32 v70, vcc, 1.0, v55, 1.0
	v_sqrt_f32_e32 v66, v54
	v_mul_f32_e32 v72, v70, v68
	v_fma_f32 v74, -v64, v72, v70
	v_fmac_f32_e32 v72, v74, v68
	v_fma_f32 v64, -v64, v72, v70
	v_add_u32_e32 v70, -1, v66
	v_fma_f32 v74, -v70, v66, v54
	v_cmp_ge_f32_e64 s[14:15], 0, v74
	v_add_u32_e32 v74, 1, v66
	v_div_fmas_f32 v64, v64, v68, v72
	v_cndmask_b32_e64 v70, v66, v70, s[14:15]
	v_fma_f32 v66, -v74, v66, v54
	v_cmp_lt_f32_e64 s[14:15], 0, v66
	v_div_fixup_f32 v68, v64, v55, 1.0
	v_pk_mul_f32 v[40:41], v[40:41], v[68:69] op_sel_hi:[1,0]
	v_cndmask_b32_e64 v66, v70, v74, s[14:15]
	v_mul_f32_e32 v70, 0x37800000, v66
	v_cndmask_b32_e64 v66, v66, v70, s[12:13]
	v_cmp_class_f32_e64 s[12:13], v54, v90
	v_pk_fma_f32 v[40:41], v[0:1], v[40:41], v[8:9]
	v_pk_mul_f32 v[42:43], v[42:43], v[68:69] op_sel_hi:[1,0]
	v_cndmask_b32_e64 v54, v66, v54, s[12:13]
	v_div_scale_f32 v66, s[12:13], v54, v54, 1.0
	v_rcp_f32_e32 v70, v66
	v_pk_fma_f32 v[42:43], v[2:3], v[42:43], v[10:11]
	v_pk_mul_f32 v[48:49], v[48:49], v[68:69] op_sel_hi:[1,0]
	v_pk_mul_f32 v[56:57], v[68:69], v[56:57] op_sel_hi:[0,1]
	v_fma_f32 v55, -v66, v70, 1.0
	v_fmac_f32_e32 v70, v55, v70
	v_div_scale_f32 v55, vcc, 1.0, v54, 1.0
	v_mul_f32_e32 v64, v55, v70
	v_fma_f32 v72, -v66, v64, v55
	v_fmac_f32_e32 v64, v72, v70
	v_fma_f32 v55, -v66, v64, v55
	v_div_fmas_f32 v55, v55, v70, v64
	v_div_fixup_f32 v70, v55, v54, 1.0
	v_pk_mul_f32 v[44:45], v[44:45], v[70:71] op_sel_hi:[1,0]
	v_mov_b32_e32 v64, 0
	v_pk_mul_f32 v[54:55], v[46:47], v[70:71] op_sel_hi:[1,0]
	v_pk_fma_f32 v[46:47], v[0:1], v[44:45], v[8:9]
	v_cvt_pk_fp8_f32 v64, v40, v41
	v_mov_b32_e32 v66, 0
	v_cvt_pk_fp8_f32 v66, v46, v47
	v_pk_fma_f32 v[44:45], v[2:3], v[54:55], v[10:11]
	v_cvt_pk_fp8_f32 v64, v42, v43 op_sel:[0,0,1]
	v_cvt_pk_bf16_f32 v54, v40, v41
	v_cvt_pk_bf16_f32 v55, v42, v43
	v_cvt_pk_fp8_f32 v66, v44, v45 op_sel:[0,0,1]
	global_store_dwordx2 v[96:97], v[54:55], off
	v_cvt_pk_bf16_f32 v54, v46, v47
	v_cvt_pk_bf16_f32 v55, v44, v45
	global_store_dwordx2 v[98:99], v[54:55], off
	global_store_dword v[92:93], v64, off
	global_store_dword v[94:95], v66, off
	v_pk_mul_f32 v[54:55], v[50:51], v[68:69] op_sel_hi:[1,0]
	v_pk_fma_f32 v[50:51], v[4:5], v[48:49], v[12:13]
	v_pk_mul_f32 v[52:53], v[52:53], v[70:71] op_sel_hi:[1,0]
	v_mov_b32_e32 v64, 0
	v_pk_fma_f32 v[52:53], v[4:5], v[52:53], v[12:13]
	v_cvt_pk_fp8_f32 v64, v50, v51
	v_mov_b32_e32 v66, 0
	v_cvt_pk_fp8_f32 v66, v52, v53
	v_pk_fma_f32 v[54:55], v[6:7], v[54:55], v[14:15]
	v_pk_mul_f32 v[48:49], v[62:63], v[70:71] op_sel_hi:[1,0]
	v_cvt_pk_fp8_f32 v64, v54, v55 op_sel:[0,0,1]
	v_pk_fma_f32 v[48:49], v[6:7], v[48:49], v[14:15]
	v_cvt_pk_bf16_f32 v62, v50, v51
	v_cvt_pk_bf16_f32 v63, v54, v55
	v_cvt_pk_fp8_f32 v66, v48, v49 op_sel:[0,0,1]
	global_store_dwordx2 v[96:97], v[62:63], off offset:512
	v_cvt_pk_bf16_f32 v62, v52, v53
	v_cvt_pk_bf16_f32 v63, v48, v49
	global_store_dwordx2 v[98:99], v[62:63], off offset:512
	global_store_dword v[92:93], v64, off offset:256
	global_store_dword v[94:95], v66, off offset:256
	v_pk_fma_f32 v[62:63], v[16:17], v[56:57], v[24:25]
	v_pk_mul_f32 v[60:61], v[70:71], v[60:61] op_sel_hi:[0,1]
	v_mov_b32_e32 v64, 0
	v_pk_fma_f32 v[60:61], v[16:17], v[60:61], v[24:25]
	v_cvt_pk_fp8_f32 v64, v62, v63
	v_mov_b32_e32 v66, 0
	v_cvt_pk_fp8_f32 v66, v60, v61
	v_pk_mul_f32 v[58:59], v[68:69], v[58:59] op_sel_hi:[0,1]
	v_pk_fma_f32 v[58:59], v[18:19], v[58:59], v[26:27]
	v_pk_mul_f32 v[56:57], v[70:71], v[80:81] op_sel_hi:[0,1]
	v_pk_fma_f32 v[56:57], v[18:19], v[56:57], v[26:27]
	v_cvt_pk_fp8_f32 v64, v58, v59 op_sel:[0,0,1]
	v_cvt_pk_bf16_f32 v80, v62, v63
	v_cvt_pk_bf16_f32 v81, v58, v59
	v_cvt_pk_fp8_f32 v66, v56, v57 op_sel:[0,0,1]
	global_store_dwordx2 v[96:97], v[80:81], off offset:1024
	v_cvt_pk_bf16_f32 v80, v60, v61
	v_cvt_pk_bf16_f32 v81, v56, v57
	global_store_dwordx2 v[98:99], v[80:81], off offset:1024
	global_store_dword v[92:93], v64, off offset:512
	global_store_dword v[94:95], v66, off offset:512
	v_mov_b32_e32 v66, v71
	v_mov_b32_e32 v74, v79
	v_pk_mul_f32 v[66:67], v[68:69], v[66:67] op_sel_hi:[0,1]
	v_mov_b32_e32 v64, v69
	v_pk_mul_f32 v[74:75], v[70:71], v[74:75] op_sel_hi:[0,1]
	v_mov_b32_e32 v72, v77
	v_pk_mul_f32 v[64:65], v[68:69], v[64:65] op_sel_hi:[0,1]
	v_pk_fma_f32 v[68:69], v[20:21], v[66:67], v[28:29]
	v_pk_mul_f32 v[66:67], v[70:71], v[72:73] op_sel_hi:[0,1]
	v_pk_fma_f32 v[70:71], v[20:21], v[74:75], v[28:29]
	v_mov_b32_e32 v74, 0
	v_cvt_pk_fp8_f32 v74, v68, v69
	v_mov_b32_e32 v75, 0
	v_cvt_pk_fp8_f32 v75, v70, v71
	v_pk_fma_f32 v[64:65], v[22:23], v[64:65], v[30:31]
	v_pk_fma_f32 v[66:67], v[22:23], v[66:67], v[30:31]
	v_cvt_pk_fp8_f32 v74, v64, v65 op_sel:[0,0,1]
	v_cvt_pk_bf16_f32 v72, v68, v69
	v_cvt_pk_bf16_f32 v73, v64, v65
	v_cvt_pk_fp8_f32 v75, v66, v67 op_sel:[0,0,1]
	global_store_dwordx2 v[96:97], v[72:73], off offset:1536
	v_cvt_pk_bf16_f32 v72, v70, v71
	v_cvt_pk_bf16_f32 v73, v66, v67
	global_store_dwordx2 v[98:99], v[72:73], off offset:1536
	global_store_dword v[92:93], v74, off offset:768
	global_store_dword v[94:95], v75, off offset:768
	ds_read_b128 v[176:179], v88 offset:0
	ds_read_b128 v[180:183], v88 offset:1024
	ds_read_b128 v[184:187], v88 offset:2048
	ds_read_b128 v[188:191], v88 offset:3072
	ds_read_b128 v[192:195], v88 offset:4096
	ds_read_b128 v[196:199], v88 offset:5120
	ds_read_b128 v[200:203], v88 offset:6144
	ds_read_b128 v[204:207], v88 offset:7168
	s_waitcnt lgkmcnt(4)
	v_pk_mul_f32 v[208:209], v[40:41], v[176:177]
	v_pk_mul_f32 v[210:211], v[46:47], v[176:177]
	v_pk_fma_f32 v[208:209], v[42:43], v[178:179], v[208:209]
	v_pk_fma_f32 v[210:211], v[44:45], v[178:179], v[210:211]
	v_pk_fma_f32 v[208:209], v[50:51], v[180:181], v[208:209]
	v_pk_fma_f32 v[210:211], v[52:53], v[180:181], v[210:211]
	v_pk_fma_f32 v[208:209], v[54:55], v[182:183], v[208:209]
	v_pk_fma_f32 v[210:211], v[48:49], v[182:183], v[210:211]
	v_pk_fma_f32 v[208:209], v[62:63], v[184:185], v[208:209]
	v_pk_fma_f32 v[210:211], v[60:61], v[184:185], v[210:211]
	v_pk_fma_f32 v[208:209], v[58:59], v[186:187], v[208:209]
	v_pk_fma_f32 v[210:211], v[56:57], v[186:187], v[210:211]
	v_pk_fma_f32 v[208:209], v[68:69], v[188:189], v[208:209]
	v_pk_fma_f32 v[210:211], v[70:71], v[188:189], v[210:211]
	v_pk_fma_f32 v[208:209], v[64:65], v[190:191], v[208:209]
	v_pk_fma_f32 v[210:211], v[66:67], v[190:191], v[210:211]
	v_add_f32_e32 v142, v208, v209
	v_add_f32_e32 v143, v210, v211
	ds_read_b128 v[176:179], v88 offset:8192
	ds_read_b128 v[180:183], v88 offset:9216
	ds_read_b128 v[184:187], v88 offset:10240
	ds_read_b128 v[188:191], v88 offset:11264
	s_waitcnt lgkmcnt(4)
	v_pk_mul_f32 v[208:209], v[40:41], v[192:193]
	v_pk_mul_f32 v[210:211], v[46:47], v[192:193]
	v_pk_fma_f32 v[208:209], v[42:43], v[194:195], v[208:209]
	v_pk_fma_f32 v[210:211], v[44:45], v[194:195], v[210:211]
	v_pk_fma_f32 v[208:209], v[50:51], v[196:197], v[208:209]
	v_pk_fma_f32 v[210:211], v[52:53], v[196:197], v[210:211]
	v_pk_fma_f32 v[208:209], v[54:55], v[198:199], v[208:209]
	v_pk_fma_f32 v[210:211], v[48:49], v[198:199], v[210:211]
	v_pk_fma_f32 v[208:209], v[62:63], v[200:201], v[208:209]
	v_pk_fma_f32 v[210:211], v[60:61], v[200:201], v[210:211]
	v_pk_fma_f32 v[208:209], v[58:59], v[202:203], v[208:209]
	v_pk_fma_f32 v[210:211], v[56:57], v[202:203], v[210:211]
	v_pk_fma_f32 v[208:209], v[68:69], v[204:205], v[208:209]
	v_pk_fma_f32 v[210:211], v[70:71], v[204:205], v[210:211]
	v_pk_fma_f32 v[208:209], v[64:65], v[206:207], v[208:209]
	v_pk_fma_f32 v[210:211], v[66:67], v[206:207], v[210:211]
	v_add_f32_e32 v144, v208, v209
	v_add_f32_e32 v145, v210, v211
	ds_read_b128 v[192:195], v88 offset:12288
	ds_read_b128 v[196:199], v88 offset:13312
	ds_read_b128 v[200:203], v88 offset:14336
	ds_read_b128 v[204:207], v88 offset:15360
	s_waitcnt lgkmcnt(4)
	v_pk_mul_f32 v[208:209], v[40:41], v[176:177]
	v_pk_mul_f32 v[210:211], v[46:47], v[176:177]
	v_pk_fma_f32 v[208:209], v[42:43], v[178:179], v[208:209]
	v_pk_fma_f32 v[210:211], v[44:45], v[178:179], v[210:211]
	v_pk_fma_f32 v[208:209], v[50:51], v[180:181], v[208:209]
	v_pk_fma_f32 v[210:211], v[52:53], v[180:181], v[210:211]
	v_pk_fma_f32 v[208:209], v[54:55], v[182:183], v[208:209]
	v_pk_fma_f32 v[210:211], v[48:49], v[182:183], v[210:211]
	v_pk_fma_f32 v[208:209], v[62:63], v[184:185], v[208:209]
	v_pk_fma_f32 v[210:211], v[60:61], v[184:185], v[210:211]
	v_pk_fma_f32 v[208:209], v[58:59], v[186:187], v[208:209]
	v_pk_fma_f32 v[210:211], v[56:57], v[186:187], v[210:211]
	v_pk_fma_f32 v[208:209], v[68:69], v[188:189], v[208:209]
	v_pk_fma_f32 v[210:211], v[70:71], v[188:189], v[210:211]
	v_pk_fma_f32 v[208:209], v[64:65], v[190:191], v[208:209]
	v_pk_fma_f32 v[210:211], v[66:67], v[190:191], v[210:211]
	v_add_f32_e32 v146, v208, v209
	v_add_f32_e32 v147, v210, v211
	ds_read_b128 v[176:179], v88 offset:16384
	ds_read_b128 v[180:183], v88 offset:17408
	ds_read_b128 v[184:187], v88 offset:18432
	ds_read_b128 v[188:191], v88 offset:19456
	s_waitcnt lgkmcnt(4)
	v_pk_mul_f32 v[208:209], v[40:41], v[192:193]
	v_pk_mul_f32 v[210:211], v[46:47], v[192:193]
	v_pk_fma_f32 v[208:209], v[42:43], v[194:195], v[208:209]
	v_pk_fma_f32 v[210:211], v[44:45], v[194:195], v[210:211]
	v_pk_fma_f32 v[208:209], v[50:51], v[196:197], v[208:209]
	v_pk_fma_f32 v[210:211], v[52:53], v[196:197], v[210:211]
	v_pk_fma_f32 v[208:209], v[54:55], v[198:199], v[208:209]
	v_pk_fma_f32 v[210:211], v[48:49], v[198:199], v[210:211]
	v_pk_fma_f32 v[208:209], v[62:63], v[200:201], v[208:209]
	v_pk_fma_f32 v[210:211], v[60:61], v[200:201], v[210:211]
	v_pk_fma_f32 v[208:209], v[58:59], v[202:203], v[208:209]
	v_pk_fma_f32 v[210:211], v[56:57], v[202:203], v[210:211]
	v_pk_fma_f32 v[208:209], v[68:69], v[204:205], v[208:209]
	v_pk_fma_f32 v[210:211], v[70:71], v[204:205], v[210:211]
	v_pk_fma_f32 v[208:209], v[64:65], v[206:207], v[208:209]
	v_pk_fma_f32 v[210:211], v[66:67], v[206:207], v[210:211]
	v_add_f32_e32 v148, v208, v209
	v_add_f32_e32 v149, v210, v211
	ds_read_b128 v[192:195], v88 offset:20480
	ds_read_b128 v[196:199], v88 offset:21504
	ds_read_b128 v[200:203], v88 offset:22528
	ds_read_b128 v[204:207], v88 offset:23552
	s_waitcnt lgkmcnt(4)
	v_pk_mul_f32 v[208:209], v[40:41], v[176:177]
	v_pk_mul_f32 v[210:211], v[46:47], v[176:177]
	v_pk_fma_f32 v[208:209], v[42:43], v[178:179], v[208:209]
	v_pk_fma_f32 v[210:211], v[44:45], v[178:179], v[210:211]
	v_pk_fma_f32 v[208:209], v[50:51], v[180:181], v[208:209]
	v_pk_fma_f32 v[210:211], v[52:53], v[180:181], v[210:211]
	v_pk_fma_f32 v[208:209], v[54:55], v[182:183], v[208:209]
	v_pk_fma_f32 v[210:211], v[48:49], v[182:183], v[210:211]
	v_pk_fma_f32 v[208:209], v[62:63], v[184:185], v[208:209]
	v_pk_fma_f32 v[210:211], v[60:61], v[184:185], v[210:211]
	v_pk_fma_f32 v[208:209], v[58:59], v[186:187], v[208:209]
	v_pk_fma_f32 v[210:211], v[56:57], v[186:187], v[210:211]
	v_pk_fma_f32 v[208:209], v[68:69], v[188:189], v[208:209]
	v_pk_fma_f32 v[210:211], v[70:71], v[188:189], v[210:211]
	v_pk_fma_f32 v[208:209], v[64:65], v[190:191], v[208:209]
	v_pk_fma_f32 v[210:211], v[66:67], v[190:191], v[210:211]
	v_add_f32_e32 v150, v208, v209
	v_add_f32_e32 v151, v210, v211
	ds_read_b128 v[176:179], v88 offset:24576
	ds_read_b128 v[180:183], v88 offset:25600
	ds_read_b128 v[184:187], v88 offset:26624
	ds_read_b128 v[188:191], v88 offset:27648
	s_waitcnt lgkmcnt(4)
	v_pk_mul_f32 v[208:209], v[40:41], v[192:193]
	v_pk_mul_f32 v[210:211], v[46:47], v[192:193]
	v_pk_fma_f32 v[208:209], v[42:43], v[194:195], v[208:209]
	v_pk_fma_f32 v[210:211], v[44:45], v[194:195], v[210:211]
	v_pk_fma_f32 v[208:209], v[50:51], v[196:197], v[208:209]
	v_pk_fma_f32 v[210:211], v[52:53], v[196:197], v[210:211]
	v_pk_fma_f32 v[208:209], v[54:55], v[198:199], v[208:209]
	v_pk_fma_f32 v[210:211], v[48:49], v[198:199], v[210:211]
	v_pk_fma_f32 v[208:209], v[62:63], v[200:201], v[208:209]
	v_pk_fma_f32 v[210:211], v[60:61], v[200:201], v[210:211]
	v_pk_fma_f32 v[208:209], v[58:59], v[202:203], v[208:209]
	v_pk_fma_f32 v[210:211], v[56:57], v[202:203], v[210:211]
	v_pk_fma_f32 v[208:209], v[68:69], v[204:205], v[208:209]
	v_pk_fma_f32 v[210:211], v[70:71], v[204:205], v[210:211]
	v_pk_fma_f32 v[208:209], v[64:65], v[206:207], v[208:209]
	v_pk_fma_f32 v[210:211], v[66:67], v[206:207], v[210:211]
	v_add_f32_e32 v152, v208, v209
	v_add_f32_e32 v153, v210, v211
	ds_read_b128 v[192:195], v88 offset:28672
	ds_read_b128 v[196:199], v88 offset:29696
	ds_read_b128 v[200:203], v88 offset:30720
	ds_read_b128 v[204:207], v88 offset:31744
	s_waitcnt lgkmcnt(4)
	v_pk_mul_f32 v[208:209], v[40:41], v[176:177]
	v_pk_mul_f32 v[210:211], v[46:47], v[176:177]
	v_pk_fma_f32 v[208:209], v[42:43], v[178:179], v[208:209]
	v_pk_fma_f32 v[210:211], v[44:45], v[178:179], v[210:211]
	v_pk_fma_f32 v[208:209], v[50:51], v[180:181], v[208:209]
	v_pk_fma_f32 v[210:211], v[52:53], v[180:181], v[210:211]
	v_pk_fma_f32 v[208:209], v[54:55], v[182:183], v[208:209]
	v_pk_fma_f32 v[210:211], v[48:49], v[182:183], v[210:211]
	v_pk_fma_f32 v[208:209], v[62:63], v[184:185], v[208:209]
	v_pk_fma_f32 v[210:211], v[60:61], v[184:185], v[210:211]
	v_pk_fma_f32 v[208:209], v[58:59], v[186:187], v[208:209]
	v_pk_fma_f32 v[210:211], v[56:57], v[186:187], v[210:211]
	v_pk_fma_f32 v[208:209], v[68:69], v[188:189], v[208:209]
	v_pk_fma_f32 v[210:211], v[70:71], v[188:189], v[210:211]
	v_pk_fma_f32 v[208:209], v[64:65], v[190:191], v[208:209]
	v_pk_fma_f32 v[210:211], v[66:67], v[190:191], v[210:211]
	v_add_f32_e32 v154, v208, v209
	v_add_f32_e32 v155, v210, v211
	ds_read_b128 v[176:179], v88 offset:32768
	ds_read_b128 v[180:183], v88 offset:33792
	ds_read_b128 v[184:187], v88 offset:34816
	ds_read_b128 v[188:191], v88 offset:35840
	s_waitcnt lgkmcnt(4)
	v_pk_mul_f32 v[208:209], v[40:41], v[192:193]
	v_pk_mul_f32 v[210:211], v[46:47], v[192:193]
	v_pk_fma_f32 v[208:209], v[42:43], v[194:195], v[208:209]
	v_pk_fma_f32 v[210:211], v[44:45], v[194:195], v[210:211]
	v_pk_fma_f32 v[208:209], v[50:51], v[196:197], v[208:209]
	v_pk_fma_f32 v[210:211], v[52:53], v[196:197], v[210:211]
	v_pk_fma_f32 v[208:209], v[54:55], v[198:199], v[208:209]
	v_pk_fma_f32 v[210:211], v[48:49], v[198:199], v[210:211]
	v_pk_fma_f32 v[208:209], v[62:63], v[200:201], v[208:209]
	v_pk_fma_f32 v[210:211], v[60:61], v[200:201], v[210:211]
	v_pk_fma_f32 v[208:209], v[58:59], v[202:203], v[208:209]
	v_pk_fma_f32 v[210:211], v[56:57], v[202:203], v[210:211]
	v_pk_fma_f32 v[208:209], v[68:69], v[204:205], v[208:209]
	v_pk_fma_f32 v[210:211], v[70:71], v[204:205], v[210:211]
	v_pk_fma_f32 v[208:209], v[64:65], v[206:207], v[208:209]
	v_pk_fma_f32 v[210:211], v[66:67], v[206:207], v[210:211]
	v_add_f32_e32 v156, v208, v209
	v_add_f32_e32 v157, v210, v211
	ds_read_b128 v[192:195], v88 offset:36864
	ds_read_b128 v[196:199], v88 offset:37888
	ds_read_b128 v[200:203], v88 offset:38912
	ds_read_b128 v[204:207], v88 offset:39936
	s_waitcnt lgkmcnt(4)
	v_pk_mul_f32 v[208:209], v[40:41], v[176:177]
	v_pk_mul_f32 v[210:211], v[46:47], v[176:177]
	v_pk_fma_f32 v[208:209], v[42:43], v[178:179], v[208:209]
	v_pk_fma_f32 v[210:211], v[44:45], v[178:179], v[210:211]
	v_pk_fma_f32 v[208:209], v[50:51], v[180:181], v[208:209]
	v_pk_fma_f32 v[210:211], v[52:53], v[180:181], v[210:211]
	v_pk_fma_f32 v[208:209], v[54:55], v[182:183], v[208:209]
	v_pk_fma_f32 v[210:211], v[48:49], v[182:183], v[210:211]
	v_pk_fma_f32 v[208:209], v[62:63], v[184:185], v[208:209]
	v_pk_fma_f32 v[210:211], v[60:61], v[184:185], v[210:211]
	v_pk_fma_f32 v[208:209], v[58:59], v[186:187], v[208:209]
	v_pk_fma_f32 v[210:211], v[56:57], v[186:187], v[210:211]
	v_pk_fma_f32 v[208:209], v[68:69], v[188:189], v[208:209]
	v_pk_fma_f32 v[210:211], v[70:71], v[188:189], v[210:211]
	v_pk_fma_f32 v[208:209], v[64:65], v[190:191], v[208:209]
	v_pk_fma_f32 v[210:211], v[66:67], v[190:191], v[210:211]
	v_add_f32_e32 v158, v208, v209
	v_add_f32_e32 v159, v210, v211
	ds_read_b128 v[176:179], v88 offset:40960
	ds_read_b128 v[180:183], v88 offset:41984
	ds_read_b128 v[184:187], v88 offset:43008
	ds_read_b128 v[188:191], v88 offset:44032
	s_waitcnt lgkmcnt(4)
	v_pk_mul_f32 v[208:209], v[40:41], v[192:193]
	v_pk_mul_f32 v[210:211], v[46:47], v[192:193]
	v_pk_fma_f32 v[208:209], v[42:43], v[194:195], v[208:209]
	v_pk_fma_f32 v[210:211], v[44:45], v[194:195], v[210:211]
	v_pk_fma_f32 v[208:209], v[50:51], v[196:197], v[208:209]
	v_pk_fma_f32 v[210:211], v[52:53], v[196:197], v[210:211]
	v_pk_fma_f32 v[208:209], v[54:55], v[198:199], v[208:209]
	v_pk_fma_f32 v[210:211], v[48:49], v[198:199], v[210:211]
	v_pk_fma_f32 v[208:209], v[62:63], v[200:201], v[208:209]
	v_pk_fma_f32 v[210:211], v[60:61], v[200:201], v[210:211]
	v_pk_fma_f32 v[208:209], v[58:59], v[202:203], v[208:209]
	v_pk_fma_f32 v[210:211], v[56:57], v[202:203], v[210:211]
	v_pk_fma_f32 v[208:209], v[68:69], v[204:205], v[208:209]
	v_pk_fma_f32 v[210:211], v[70:71], v[204:205], v[210:211]
	v_pk_fma_f32 v[208:209], v[64:65], v[206:207], v[208:209]
	v_pk_fma_f32 v[210:211], v[66:67], v[206:207], v[210:211]
	v_add_f32_e32 v160, v208, v209
	v_add_f32_e32 v161, v210, v211
	ds_read_b128 v[192:195], v88 offset:45056
	ds_read_b128 v[196:199], v88 offset:46080
	ds_read_b128 v[200:203], v88 offset:47104
	ds_read_b128 v[204:207], v88 offset:48128
	s_waitcnt lgkmcnt(4)
	v_pk_mul_f32 v[208:209], v[40:41], v[176:177]
	v_pk_mul_f32 v[210:211], v[46:47], v[176:177]
	v_pk_fma_f32 v[208:209], v[42:43], v[178:179], v[208:209]
	v_pk_fma_f32 v[210:211], v[44:45], v[178:179], v[210:211]
	v_pk_fma_f32 v[208:209], v[50:51], v[180:181], v[208:209]
	v_pk_fma_f32 v[210:211], v[52:53], v[180:181], v[210:211]
	v_pk_fma_f32 v[208:209], v[54:55], v[182:183], v[208:209]
	v_pk_fma_f32 v[210:211], v[48:49], v[182:183], v[210:211]
	v_pk_fma_f32 v[208:209], v[62:63], v[184:185], v[208:209]
	v_pk_fma_f32 v[210:211], v[60:61], v[184:185], v[210:211]
	v_pk_fma_f32 v[208:209], v[58:59], v[186:187], v[208:209]
	v_pk_fma_f32 v[210:211], v[56:57], v[186:187], v[210:211]
	v_pk_fma_f32 v[208:209], v[68:69], v[188:189], v[208:209]
	v_pk_fma_f32 v[210:211], v[70:71], v[188:189], v[210:211]
	v_pk_fma_f32 v[208:209], v[64:65], v[190:191], v[208:209]
	v_pk_fma_f32 v[210:211], v[66:67], v[190:191], v[210:211]
	v_add_f32_e32 v162, v208, v209
	v_add_f32_e32 v163, v210, v211
	ds_read_b128 v[176:179], v88 offset:49152
	ds_read_b128 v[180:183], v88 offset:50176
	ds_read_b128 v[184:187], v88 offset:51200
	ds_read_b128 v[188:191], v88 offset:52224
	s_waitcnt lgkmcnt(4)
	v_pk_mul_f32 v[208:209], v[40:41], v[192:193]
	v_pk_mul_f32 v[210:211], v[46:47], v[192:193]
	v_pk_fma_f32 v[208:209], v[42:43], v[194:195], v[208:209]
	v_pk_fma_f32 v[210:211], v[44:45], v[194:195], v[210:211]
	v_pk_fma_f32 v[208:209], v[50:51], v[196:197], v[208:209]
	v_pk_fma_f32 v[210:211], v[52:53], v[196:197], v[210:211]
	v_pk_fma_f32 v[208:209], v[54:55], v[198:199], v[208:209]
	v_pk_fma_f32 v[210:211], v[48:49], v[198:199], v[210:211]
	v_pk_fma_f32 v[208:209], v[62:63], v[200:201], v[208:209]
	v_pk_fma_f32 v[210:211], v[60:61], v[200:201], v[210:211]
	v_pk_fma_f32 v[208:209], v[58:59], v[202:203], v[208:209]
	v_pk_fma_f32 v[210:211], v[56:57], v[202:203], v[210:211]
	v_pk_fma_f32 v[208:209], v[68:69], v[204:205], v[208:209]
	v_pk_fma_f32 v[210:211], v[70:71], v[204:205], v[210:211]
	v_pk_fma_f32 v[208:209], v[64:65], v[206:207], v[208:209]
	v_pk_fma_f32 v[210:211], v[66:67], v[206:207], v[210:211]
	v_add_f32_e32 v164, v208, v209
	v_add_f32_e32 v165, v210, v211
	ds_read_b128 v[192:195], v88 offset:53248
	ds_read_b128 v[196:199], v88 offset:54272
	ds_read_b128 v[200:203], v88 offset:55296
	ds_read_b128 v[204:207], v88 offset:56320
	s_waitcnt lgkmcnt(4)
	v_pk_mul_f32 v[208:209], v[40:41], v[176:177]
	v_pk_mul_f32 v[210:211], v[46:47], v[176:177]
	v_pk_fma_f32 v[208:209], v[42:43], v[178:179], v[208:209]
	v_pk_fma_f32 v[210:211], v[44:45], v[178:179], v[210:211]
	v_pk_fma_f32 v[208:209], v[50:51], v[180:181], v[208:209]
	v_pk_fma_f32 v[210:211], v[52:53], v[180:181], v[210:211]
	v_pk_fma_f32 v[208:209], v[54:55], v[182:183], v[208:209]
	v_pk_fma_f32 v[210:211], v[48:49], v[182:183], v[210:211]
	v_pk_fma_f32 v[208:209], v[62:63], v[184:185], v[208:209]
	v_pk_fma_f32 v[210:211], v[60:61], v[184:185], v[210:211]
	v_pk_fma_f32 v[208:209], v[58:59], v[186:187], v[208:209]
	v_pk_fma_f32 v[210:211], v[56:57], v[186:187], v[210:211]
	v_pk_fma_f32 v[208:209], v[68:69], v[188:189], v[208:209]
	v_pk_fma_f32 v[210:211], v[70:71], v[188:189], v[210:211]
	v_pk_fma_f32 v[208:209], v[64:65], v[190:191], v[208:209]
	v_pk_fma_f32 v[210:211], v[66:67], v[190:191], v[210:211]
	v_add_f32_e32 v166, v208, v209
	v_add_f32_e32 v167, v210, v211
	ds_read_b128 v[176:179], v88 offset:57344
	ds_read_b128 v[180:183], v88 offset:58368
	ds_read_b128 v[184:187], v88 offset:59392
	ds_read_b128 v[188:191], v88 offset:60416
	s_waitcnt lgkmcnt(4)
	v_pk_mul_f32 v[208:209], v[40:41], v[192:193]
	v_pk_mul_f32 v[210:211], v[46:47], v[192:193]
	v_pk_fma_f32 v[208:209], v[42:43], v[194:195], v[208:209]
	v_pk_fma_f32 v[210:211], v[44:45], v[194:195], v[210:211]
	v_pk_fma_f32 v[208:209], v[50:51], v[196:197], v[208:209]
	v_pk_fma_f32 v[210:211], v[52:53], v[196:197], v[210:211]
	v_pk_fma_f32 v[208:209], v[54:55], v[198:199], v[208:209]
	v_pk_fma_f32 v[210:211], v[48:49], v[198:199], v[210:211]
	v_pk_fma_f32 v[208:209], v[62:63], v[200:201], v[208:209]
	v_pk_fma_f32 v[210:211], v[60:61], v[200:201], v[210:211]
	v_pk_fma_f32 v[208:209], v[58:59], v[202:203], v[208:209]
	v_pk_fma_f32 v[210:211], v[56:57], v[202:203], v[210:211]
	v_pk_fma_f32 v[208:209], v[68:69], v[204:205], v[208:209]
	v_pk_fma_f32 v[210:211], v[70:71], v[204:205], v[210:211]
	v_pk_fma_f32 v[208:209], v[64:65], v[206:207], v[208:209]
	v_pk_fma_f32 v[210:211], v[66:67], v[206:207], v[210:211]
	v_add_f32_e32 v168, v208, v209
	v_add_f32_e32 v169, v210, v211
	ds_read_b128 v[192:195], v88 offset:61440
	ds_read_b128 v[196:199], v88 offset:62464
	ds_read_b128 v[200:203], v88 offset:63488
	ds_read_b128 v[204:207], v88 offset:64512
	s_waitcnt lgkmcnt(4)
	v_pk_mul_f32 v[208:209], v[40:41], v[176:177]
	v_pk_mul_f32 v[210:211], v[46:47], v[176:177]
	v_pk_fma_f32 v[208:209], v[42:43], v[178:179], v[208:209]
	v_pk_fma_f32 v[210:211], v[44:45], v[178:179], v[210:211]
	v_pk_fma_f32 v[208:209], v[50:51], v[180:181], v[208:209]
	v_pk_fma_f32 v[210:211], v[52:53], v[180:181], v[210:211]
	v_pk_fma_f32 v[208:209], v[54:55], v[182:183], v[208:209]
	v_pk_fma_f32 v[210:211], v[48:49], v[182:183], v[210:211]
	v_pk_fma_f32 v[208:209], v[62:63], v[184:185], v[208:209]
	v_pk_fma_f32 v[210:211], v[60:61], v[184:185], v[210:211]
	v_pk_fma_f32 v[208:209], v[58:59], v[186:187], v[208:209]
	v_pk_fma_f32 v[210:211], v[56:57], v[186:187], v[210:211]
	v_pk_fma_f32 v[208:209], v[68:69], v[188:189], v[208:209]
	v_pk_fma_f32 v[210:211], v[70:71], v[188:189], v[210:211]
	v_pk_fma_f32 v[208:209], v[64:65], v[190:191], v[208:209]
	v_pk_fma_f32 v[210:211], v[66:67], v[190:191], v[210:211]
	v_add_f32_e32 v170, v208, v209
	v_add_f32_e32 v171, v210, v211
	s_waitcnt lgkmcnt(0)
	v_pk_mul_f32 v[208:209], v[40:41], v[192:193]
	v_pk_mul_f32 v[210:211], v[46:47], v[192:193]
	v_pk_fma_f32 v[208:209], v[42:43], v[194:195], v[208:209]
	v_pk_fma_f32 v[210:211], v[44:45], v[194:195], v[210:211]
	v_pk_fma_f32 v[208:209], v[50:51], v[196:197], v[208:209]
	v_pk_fma_f32 v[210:211], v[52:53], v[196:197], v[210:211]
	v_pk_fma_f32 v[208:209], v[54:55], v[198:199], v[208:209]
	v_pk_fma_f32 v[210:211], v[48:49], v[198:199], v[210:211]
	v_pk_fma_f32 v[208:209], v[62:63], v[200:201], v[208:209]
	v_pk_fma_f32 v[210:211], v[60:61], v[200:201], v[210:211]
	v_pk_fma_f32 v[208:209], v[58:59], v[202:203], v[208:209]
	v_pk_fma_f32 v[210:211], v[56:57], v[202:203], v[210:211]
	v_pk_fma_f32 v[208:209], v[68:69], v[204:205], v[208:209]
	v_pk_fma_f32 v[210:211], v[70:71], v[204:205], v[210:211]
	v_pk_fma_f32 v[208:209], v[64:65], v[206:207], v[208:209]
	v_pk_fma_f32 v[210:211], v[66:67], v[206:207], v[210:211]
	v_add_f32_e32 v172, v208, v209
	v_add_f32_e32 v173, v210, v211
	v_cndmask_b32_e64 v43, v142, v158, s[0:1]
	ds_bpermute_b32 v43, v82, v43
	v_cndmask_b32_e64 v45, v144, v160, s[0:1]
	ds_bpermute_b32 v45, v82, v45
	v_cndmask_b32_e64 v46, v146, v162, s[0:1]
	ds_bpermute_b32 v46, v82, v46
	v_cndmask_b32_e64 v44, v158, v142, s[0:1]
	s_waitcnt lgkmcnt(2)
	v_add_f32_e32 v43, v44, v43
	v_cndmask_b32_e64 v44, v160, v144, s[0:1]
	s_waitcnt lgkmcnt(1)
	v_add_f32_e32 v44, v44, v45
	v_cndmask_b32_e64 v45, v162, v146, s[0:1]
	s_waitcnt lgkmcnt(0)
	v_add_f32_e32 v45, v45, v46
	v_cndmask_b32_e64 v46, v148, v164, s[0:1]
	ds_bpermute_b32 v46, v82, v46
	v_cndmask_b32_e64 v48, v150, v166, s[0:1]
	ds_bpermute_b32 v48, v82, v48
	v_cndmask_b32_e64 v49, v152, v168, s[0:1]
	ds_bpermute_b32 v49, v82, v49
	v_cndmask_b32_e64 v47, v164, v148, s[0:1]
	s_waitcnt lgkmcnt(2)
	v_add_f32_e32 v46, v47, v46
	v_cndmask_b32_e64 v47, v166, v150, s[0:1]
	s_waitcnt lgkmcnt(1)
	v_add_f32_e32 v47, v47, v48
	v_cndmask_b32_e64 v48, v168, v152, s[0:1]
	s_waitcnt lgkmcnt(0)
	v_add_f32_e32 v48, v48, v49
	v_cndmask_b32_e64 v49, v154, v170, s[0:1]
	ds_bpermute_b32 v49, v82, v49
	v_cndmask_b32_e64 v51, v156, v172, s[0:1]
	ds_bpermute_b32 v51, v82, v51
	v_cndmask_b32_e64 v50, v170, v154, s[0:1]
	v_cndmask_b32_e64 v41, v172, v156, s[0:1]
	s_waitcnt lgkmcnt(1)
	v_add_f32_e32 v49, v50, v49
	v_cndmask_b32_e64 v52, v43, v47, s[4:5]
	s_waitcnt lgkmcnt(0)
	v_add_f32_e32 v41, v41, v51
	v_cndmask_b32_e64 v43, v47, v43, s[4:5]
	v_cndmask_b32_e64 v47, v44, v48, s[4:5]
	v_cndmask_b32_e64 v44, v48, v44, s[4:5]
	v_cndmask_b32_e64 v48, v45, v49, s[4:5]
	ds_bpermute_b32 v52, v83, v52
	ds_bpermute_b32 v48, v83, v48
	v_cndmask_b32_e64 v50, v46, v41, s[4:5]
	ds_bpermute_b32 v47, v83, v47
	ds_bpermute_b32 v50, v83, v50
	v_cndmask_b32_e64 v45, v49, v45, s[4:5]
	s_waitcnt lgkmcnt(3)
	v_add_f32_e32 v43, v43, v52
	s_waitcnt lgkmcnt(2)
	v_add_f32_e32 v45, v45, v48
	v_cndmask_b32_e64 v41, v41, v46, s[4:5]
	s_waitcnt lgkmcnt(1)
	v_add_f32_e32 v44, v44, v47
	s_waitcnt lgkmcnt(0)
	v_add_f32_e32 v41, v41, v50
	v_cndmask_b32_e64 v46, v43, v45, s[6:7]
	ds_bpermute_b32 v46, v84, v46
	v_cndmask_b32_e64 v47, v44, v41, s[6:7]
	ds_bpermute_b32 v47, v84, v47
	v_cndmask_b32_e64 v42, v45, v43, s[6:7]
	v_cndmask_b32_e64 v41, v41, v44, s[6:7]
	v_cndmask_b32_e64 v44, v143, v159, s[0:1]
	s_waitcnt lgkmcnt(1)
	v_add_f32_e32 v42, v42, v46
	ds_bpermute_b32 v44, v82, v44
	v_cndmask_b32_e64 v46, v145, v161, s[0:1]
	s_waitcnt lgkmcnt(1)
	v_add_f32_e32 v41, v41, v47
	ds_bpermute_b32 v46, v82, v46
	v_cndmask_b32_e64 v47, v147, v163, s[0:1]
	ds_bpermute_b32 v47, v82, v47
	v_cndmask_b32_e64 v45, v159, v143, s[0:1]
	s_waitcnt lgkmcnt(2)
	v_add_f32_e32 v44, v45, v44
	v_cndmask_b32_e64 v45, v161, v145, s[0:1]
	s_waitcnt lgkmcnt(1)
	v_add_f32_e32 v45, v45, v46
	v_cndmask_b32_e64 v46, v163, v147, s[0:1]
	s_waitcnt lgkmcnt(0)
	v_add_f32_e32 v46, v46, v47
	v_cndmask_b32_e64 v47, v149, v165, s[0:1]
	ds_bpermute_b32 v47, v82, v47
	v_cndmask_b32_e64 v49, v151, v167, s[0:1]
	ds_bpermute_b32 v49, v82, v49
	v_cndmask_b32_e64 v50, v153, v169, s[0:1]
	ds_bpermute_b32 v50, v82, v50
	v_cndmask_b32_e64 v48, v165, v149, s[0:1]
	s_waitcnt lgkmcnt(2)
	v_add_f32_e32 v47, v48, v47
	v_cndmask_b32_e64 v48, v167, v151, s[0:1]
	s_waitcnt lgkmcnt(1)
	v_add_f32_e32 v48, v48, v49
	v_cndmask_b32_e64 v49, v169, v153, s[0:1]
	s_waitcnt lgkmcnt(0)
	v_add_f32_e32 v49, v49, v50
	v_cndmask_b32_e64 v50, v155, v171, s[0:1]
	v_cndmask_b32_e64 v52, v157, v173, s[0:1]
	ds_bpermute_b32 v50, v82, v50
	ds_bpermute_b32 v52, v82, v52
	v_cndmask_b32_e64 v51, v171, v155, s[0:1]
	v_cndmask_b32_e64 v40, v173, v157, s[0:1]
	v_cndmask_b32_e64 v53, v44, v48, s[4:5]
	s_waitcnt lgkmcnt(1)
	v_add_f32_e32 v50, v51, v50
	s_waitcnt lgkmcnt(0)
	v_add_f32_e32 v40, v40, v52
	v_cndmask_b32_e64 v44, v48, v44, s[4:5]
	v_cndmask_b32_e64 v48, v45, v49, s[4:5]
	v_cndmask_b32_e64 v45, v49, v45, s[4:5]
	v_cndmask_b32_e64 v49, v46, v50, s[4:5]
	v_cndmask_b32_e64 v51, v47, v40, s[4:5]
	ds_bpermute_b32 v53, v83, v53
	ds_bpermute_b32 v48, v83, v48
	ds_bpermute_b32 v49, v83, v49
	ds_bpermute_b32 v51, v83, v51
	v_cndmask_b32_e64 v46, v50, v46, s[4:5]
	v_cndmask_b32_e64 v40, v40, v47, s[4:5]
	s_waitcnt lgkmcnt(3)
	v_add_f32_e32 v44, v44, v53
	s_waitcnt lgkmcnt(2)
	v_add_f32_e32 v45, v45, v48
	s_waitcnt lgkmcnt(1)
	v_add_f32_e32 v46, v46, v49
	s_waitcnt lgkmcnt(0)
	v_add_f32_e32 v40, v40, v51
	v_cndmask_b32_e64 v47, v44, v46, s[6:7]
	v_cndmask_b32_e64 v48, v45, v40, s[6:7]
	ds_bpermute_b32 v47, v84, v47
	ds_bpermute_b32 v48, v84, v48
	v_cndmask_b32_e64 v44, v46, v44, s[6:7]
	v_cndmask_b32_e64 v40, v40, v45, s[6:7]
	v_cndmask_b32_e64 v43, v42, v41, s[8:9]
	s_waitcnt lgkmcnt(1)
	v_add_f32_e32 v44, v44, v47
	s_waitcnt lgkmcnt(0)
	v_add_f32_e32 v40, v40, v48
	ds_bpermute_b32 v43, v85, v43
	v_cndmask_b32_e64 v45, v44, v40, s[8:9]
	ds_bpermute_b32 v45, v85, v45
	v_cndmask_b32_e64 v41, v41, v42, s[8:9]
	v_cndmask_b32_e64 v40, v40, v44, s[8:9]
	s_waitcnt lgkmcnt(1)
	v_add_f32_e32 v41, v41, v43
	ds_bpermute_b32 v42, v86, v41
	s_waitcnt lgkmcnt(1)
	v_add_f32_e32 v40, v40, v45
	ds_bpermute_b32 v43, v86, v40
	s_waitcnt lgkmcnt(1)
	v_add_f32_e32 v41, v41, v42
	ds_bpermute_b32 v42, v87, v41
	s_waitcnt lgkmcnt(1)
	v_add_f32_e32 v40, v40, v43
	ds_bpermute_b32 v43, v87, v40
	s_waitcnt lgkmcnt(1)
	v_add_f32_e32 v41, v41, v42
	ds_bpermute_b32 v42, v82, v41
	s_waitcnt lgkmcnt(1)
	v_add_f32_e32 v40, v40, v43
	ds_bpermute_b32 v43, v82, v40
	s_waitcnt lgkmcnt(1)
	v_max_f32_e32 v42, v42, v42
	v_max_f32_e32 v42, v41, v42
	s_waitcnt lgkmcnt(0)
	v_max_f32_e32 v43, v43, v43
	ds_bpermute_b32 v44, v83, v42
	v_max_f32_e32 v43, v40, v43
	ds_bpermute_b32 v45, v83, v43
	s_waitcnt lgkmcnt(1)
	v_max_f32_e32 v44, v44, v44
	v_max_f32_e32 v42, v42, v44
	s_waitcnt lgkmcnt(0)
	v_max_f32_e32 v44, v45, v45
	v_max_f32_e32 v43, v43, v44
	ds_bpermute_b32 v45, v84, v42
	ds_bpermute_b32 v44, v84, v43
	s_waitcnt lgkmcnt(1)
	v_max_f32_e32 v45, v45, v45
	s_waitcnt lgkmcnt(0)
	v_max_f32_e32 v44, v44, v44
	v_max_f32_e32 v42, v42, v45
	v_max_f32_e32 v43, v43, v44
	ds_bpermute_b32 v45, v85, v42
	ds_bpermute_b32 v44, v85, v43
	s_waitcnt lgkmcnt(1)
	v_max_f32_e32 v45, v45, v45
	s_waitcnt lgkmcnt(0)
	v_max_f32_e32 v44, v44, v44
	v_max_f32_e32 v42, v42, v45
	v_max_f32_e32 v43, v43, v44
	v_sub_f32_e32 v41, v41, v42
	v_sub_f32_e32 v40, v40, v43
	v_mul_f32_e32 v41, 0x3fb8aa3b, v41
	v_mul_f32_e32 v40, 0x3fb8aa3b, v40
	v_exp_f32_e32 v41, v41
	v_exp_f32_e32 v40, v40
	ds_bpermute_b32 v42, v82, v41
	ds_bpermute_b32 v43, v82, v40
	s_waitcnt lgkmcnt(1)
	v_add_f32_e32 v42, v41, v42
	s_waitcnt lgkmcnt(0)
	v_add_f32_e32 v43, v40, v43
	ds_bpermute_b32 v44, v83, v42
	ds_bpermute_b32 v45, v83, v43
	s_waitcnt lgkmcnt(1)
	v_add_f32_e32 v42, v42, v44
	s_waitcnt lgkmcnt(0)
	v_add_f32_e32 v44, v43, v45
	ds_bpermute_b32 v43, v84, v42
	ds_bpermute_b32 v45, v84, v44
	s_waitcnt lgkmcnt(1)
	v_add_f32_e32 v43, v42, v43
	s_waitcnt lgkmcnt(0)
	v_add_f32_e32 v42, v44, v45
	ds_bpermute_b32 v45, v85, v43
	ds_bpermute_b32 v44, v85, v42
	s_and_saveexec_b64 s[12:13], s[10:11]
	s_cbranch_execz .LBB0_801
	s_waitcnt lgkmcnt(1)
	v_add_f32_e32 v43, v43, v45
	v_div_scale_f32 v45, s[14:15], v43, v43, v41
	v_rcp_f32_e32 v46, v45
	s_waitcnt lgkmcnt(0)
	v_add_f32_e32 v44, v42, v44
	v_fma_f32 v42, -v45, v46, 1.0
	v_fmac_f32_e32 v46, v42, v46
	v_div_scale_f32 v42, vcc, v41, v43, v41
	v_mul_f32_e32 v47, v42, v46
	v_fma_f32 v48, -v45, v47, v42
	v_fmac_f32_e32 v47, v48, v46
	v_fma_f32 v42, -v45, v47, v42
	v_div_scale_f32 v45, s[14:15], v44, v44, v40
	v_div_fmas_f32 v42, v42, v46, v47
	v_rcp_f32_e32 v46, v45
	v_div_fixup_f32 v41, v42, v43, v41
	v_lshl_add_u64 v[42:43], s[18:19], 2, v[34:35]
	global_store_dword v[42:43], v41, off
	v_fma_f32 v41, -v45, v46, 1.0
	v_fmac_f32_e32 v46, v41, v46
	v_div_scale_f32 v41, vcc, v40, v44, v40
	v_mul_f32_e32 v42, v41, v46
	v_fma_f32 v43, -v45, v42, v41
	v_fmac_f32_e32 v42, v43, v46
	v_fma_f32 v41, -v45, v42, v41
	v_div_fmas_f32 v41, v41, v46, v42
	v_div_fixup_f32 v42, v41, v44, v40
	v_lshl_add_u64 v[40:41], s[16:17], 2, v[34:35]
	global_store_dword v[40:41], v42, off
	s_branch .LBB0_801
